# attention K tile: LDS chunk swizzle extended with row bit 4 so ds_read_b128 lane groups are bank-conflict free (was 2-way)
# baseline (speedup 1.0000x reference)
; #define LAS __attribute__((address_space(3)))
; __device__ __forceinline__ int v_st(int k, int c) { const int kk = (k & ~0xC) | ((k & 4) << 1) | ((k & 8) >> 1); return ((kk >> 3) * 4 + (c >> 5)) * 512 + ((kk & 7) * 32 + (c & 31)) * 2; }
; __device__ __forceinline__ int v_rd_base(int lane) { return ((lane & 3) << 3) | (((lane >> 2) & 3) << 6) | (((lane >> 4) & 1) << 5) | (((lane >> 5) & 1) << 8); }
; #define VMW() asm volatile("s_waitcnt vmcnt(0)" ::: "memory")
; #define SLOAD_H(Kp, Vp, k0) do { st_v0 = load8(ROW(Vp, k0, sr)); st_v1 = load8(ROW(Vp, k0, 32 + sr)); st_k0 = load8(ROW(Kp, k0, sr)); st_k1 = load8(ROW(Kp, k0, 32 + sr)); } while (0)
; __device__ __forceinline__ void block(const BlockRef& cur, const int j0, const int NT, const int split, const SplitRef sp, lptr lds, int tid) {
;     const int wid = __builtin_amdgcn_readfirstlane(tid >> 6), lane = tid & 63, r32 = lane & 31, hi = lane >> 5;
;     const int qlo = cur.P0 + wid * QBLK, qm = qlo + r32 - 4 * hi;
;     lptr V_lds = lds; lptr K_lds = lds + 2 * SHM_V;
;     LAS float* wsc = (LAS float*)(lds + OFF_WS) + wid * 64; LAS float* li_l = wsc; LAS float* al_l = wsc + 32;
;     const LAS float* Cs = (const LAS float*)(lds + OFF_CS) + 4 * hi;
;     float m_reg = -1e30f, l_reg = 0; f32x16 o[4] = {};
;     const int sr = tid >> 4, sc = (tid & 15) * 8, vst0 = v_st(sr, sc), vst1 = v_st(32 + sr, sc), kws = KSWZ(sr, sc * 2);
;     const int vb0 = (int)(unsigned)(uintptr_t)V_lds + v_rd_base(lane);
;     const bf16_t* Kh = cur.K; const bf16_t* Vh = cur.V;
;     bf16x8 qr[8], st_v0, st_v1, st_k0, st_k1;
; #pragma unroll
;     for (int d0 = 0; d0 < 8; ++d0) qr[d0] = load8(cur.Q + (size_t)(wid * QBLK + r32) * D + d0 * 16 + hi * 8);
;     SLOAD_H(Kh, Vh, j0 * KVBLK); VMW(); SWRITE_H(0);
;     SLOAD_H(Kh, Vh, (j0 + 1) * KVBLK);
; __device__ __forceinline__ void attn_phase(const bf16_t* FQ, const bf16_t* FK, const bf16_t* FV, const float* cum, const float* norms, bf16_t* Y, unsigned* qctr, unsigned* flags, float* parts, lptr lds, int tid_) {
;     ...
;         const int j0 = sh[1] & ~1, NTe = NTall - j0;
;         int jb = j0, nt = NTe;
;         if (nh == 2) { const int nA = (NTe >> 1) & ~1; if (half == 0) nt = nA; else { jb = j0 + nA; nt = NTe - nA; } }
.LBB0_861:
	v_readlane_b32 s0, v254, 50
	s_waitcnt lgkmcnt(0)
	s_barrier
	s_waitcnt vmcnt(0)
	v_mov_b32_e32 v2, s0
	ds_read_b32 v2, v2
	v_ashrrev_i32_e32 v186, 4, v174
	v_add_u32_e32 v18, 32, v186
	v_and_b32_e32 v5, 0xfffff0, v186
	v_lshlrev_b32_e32 v6, 1, v186
	s_waitcnt lgkmcnt(0)
	v_readfirstlane_b32 s89, v2
	s_and_b32 s0, s89, -2
	s_sub_i32 s1, s12, s0
	s_ashr_i32 s6, s1, 1
	s_and_b32 s81, s6, -2
	s_cmp_eq_u32 s10, 0
	s_cselect_b64 s[6:7], -1, 0
	s_and_b64 s[8:9], s[6:7], exec
	s_cselect_b32 s10, 0, s81
	s_cmp_eq_u32 s11, 2
	s_cselect_b64 s[90:91], -1, 0
	s_and_b64 s[8:9], s[90:91], exec
	s_cselect_b32 s92, s10, 0
	s_add_i32 s82, s92, s0
	s_lshl_b32 s0, s96, 20
	v_readlane_b32 s8, v255, 3
	s_add_u32 s10, s8, s0
	v_readlane_b32 s8, v255, 4
	s_addc_u32 s11, s8, 0
	v_readlane_b32 s8, v255, 5
	s_add_u32 s72, s8, s0
	v_readlane_b32 s8, v255, 6
	s_addc_u32 s73, s8, 0
	v_readlane_b32 s8, v255, 7
	v_lshlrev_b32_e32 v2, 3, v174
	s_add_u32 s40, s8, s0
	v_readlane_b32 s0, v255, 8
	v_and_b32_e32 v3, 0x78, v2
	s_addc_u32 s41, s0, 0
	s_ashr_i32 s75, s74, 31
	v_lshlrev_b32_e32 v50, 1, v3
	v_and_b32_e32 v3, 0xfffff0, v18
	v_lshlrev_b32_e32 v8, 1, v18
	s_lshl_b64 s[8:9], s[74:75], 16
	v_and_or_b32 v5, v6, 8, v5
	v_and_or_b32 v3, v8, 8, v3
	s_add_u32 s8, s10, s8
	v_readfirstlane_b32 s85, v174
	v_lshrrev_b32_e32 v6, 1, v186
	v_lshrrev_b32_e32 v5, 1, v5
	v_bfe_u32 v2, v2, 5, 2
	v_and_b32_e32 v7, 3, v186
	v_lshrrev_b32_e32 v3, 1, v3
	s_addc_u32 s9, s11, s9
	s_ashr_i32 s86, s85, 6
	v_or_b32_e32 v5, v5, v2
	v_and_or_b32 v6, v6, 4, v7
	v_or_b32_e32 v2, v3, v2
	v_and_b32_e32 v219, 31, v174
	s_lshl_b32 s0, s86, 5
	v_lshlrev_b32_e32 v6, 6, v6
	v_and_b32_e32 v7, 48, v50
	v_lshlrev_b32_e32 v2, 9, v2
	v_or3_b32 v19, v2, v6, v7
	v_or_b32_e32 v2, s0, v219
	v_ashrrev_i32_e32 v3, 31, v2
	v_lshrrev_b32_e32 v217, 5, v216
	v_lshlrev_b64 v[2:3], 8, v[2:3]
	v_lshl_add_u64 v[2:3], s[8:9], 0, v[2:3]
	v_lshlrev_b32_e32 v162, 4, v217
	v_lshl_add_u64 v[2:3], v[2:3], 0, v[162:163]
	s_add_i32 s8, 0, 0x10800
	v_and_b32_e32 v8, 0x70, v174
	global_load_dwordx4 v[142:145], v[2:3], off
	global_load_dwordx4 v[138:141], v[2:3], off offset:32
	global_load_dwordx4 v[134:137], v[2:3], off offset:64
	global_load_dwordx4 v[130:133], v[2:3], off offset:96
	global_load_dwordx4 v[126:129], v[2:3], off offset:128
	global_load_dwordx4 v[122:125], v[2:3], off offset:160
	global_load_dwordx4 v[118:121], v[2:3], off offset:192
	global_load_dwordx4 v[114:117], v[2:3], off offset:224
	v_add_u32_e32 v182, s8, v162
	v_lshlrev_b32_e32 v2, 8, v186
	s_lshl_b32 s8, s82, 6
	v_bitop3_b32 v21, v50, v2, v8 bitop3:0xde
	v_add_u32_e32 v2, s8, v186
	v_ashrrev_i32_e32 v3, 31, v2
	v_lshlrev_b64 v[10:11], 8, v[2:3]
	s_lshl_b32 s10, s74, 8
	v_lshlrev_b32_e32 v175, 2, v217
	v_lshlrev_b32_e32 v5, 9, v5
	v_lshl_add_u64 v[2:3], s[40:41], 0, v[10:11]
	v_mov_b32_e32 v51, v163
	v_sub_u32_e32 v4, v219, v175
	s_add_i32 s80, s0, s10
	v_or3_b32 v20, v5, v6, v7
	v_lshl_add_u64 v[2:3], v[2:3], 0, v[50:51]
	v_add_u32_e32 v6, s8, v18
	v_add_u32_e32 v180, s80, v4
	global_load_dwordx4 v[2:5], v[2:3], off
	v_ashrrev_i32_e32 v7, 31, v6
	v_lshlrev_b64 v[14:15], 8, v[6:7]
	v_lshl_add_u64 v[6:7], s[40:41], 0, v[14:15]
	v_lshl_add_u64 v[10:11], s[72:73], 0, v[10:11]
	v_lshl_add_u64 v[6:7], v[6:7], 0, v[50:51]
	v_lshl_add_u64 v[10:11], v[10:11], 0, v[50:51]
	v_lshl_add_u64 v[14:15], s[72:73], 0, v[14:15]
	global_load_dwordx4 v[6:9], v[6:7], off
	v_lshl_add_u64 v[14:15], v[14:15], 0, v[50:51]
	global_load_dwordx4 v[10:13], v[10:11], off
	v_add_u32_e32 v188, 0, v20
	global_load_dwordx4 v[14:17], v[14:15], off
	s_or_b32 s9, s8, 64
	s_waitcnt vmcnt(0)
	v_add_u32_e32 v189, 0, v19
	v_add_u32_e32 v190, 0, v21
	v_and_b32_e32 v215, 0x100, v174
	v_lshrrev_b32_e32 v215, 1, v215
	v_xor_b32_e32 v190, v190, v215
	s_waitcnt vmcnt(3)
	ds_write_b128 v188, v[2:5]
	v_add_u32_e32 v2, s9, v186
	v_ashrrev_i32_e32 v3, 31, v2
	v_lshlrev_b64 v[2:3], 8, v[2:3]
	v_lshl_add_u64 v[4:5], s[40:41], 0, v[2:3]
	v_lshl_add_u64 v[2:3], s[72:73], 0, v[2:3]
	v_lshl_add_u64 v[4:5], v[4:5], 0, v[50:51]
	v_lshl_add_u64 v[2:3], v[2:3], 0, v[50:51]
	s_waitcnt vmcnt(2)
	ds_write_b128 v189, v[6:9]
	s_waitcnt vmcnt(1)
	ds_write_b128 v190, v[10:13] offset:32768
	s_waitcnt vmcnt(0)
	ds_write_b128 v190, v[14:17] offset:40960
	global_load_dwordx4 v[34:37], v[4:5], off
	global_load_dwordx4 v[42:45], v[2:3], off
	v_add_u32_e32 v4, s9, v18
	v_ashrrev_i32_e32 v5, 31, v4
	v_lshlrev_b64 v[4:5], 8, v[4:5]
	v_lshl_add_u64 v[6:7], s[40:41], 0, v[4:5]
	v_lshl_add_u64 v[2:3], s[72:73], 0, v[4:5]
	v_lshl_add_u64 v[6:7], v[6:7], 0, v[50:51]
	v_lshl_add_u64 v[2:3], v[2:3], 0, v[50:51]
	global_load_dwordx4 v[38:41], v[6:7], off
	global_load_dwordx4 v[46:49], v[2:3], off
	s_waitcnt lgkmcnt(0)
	s_barrier
; #define LAS __attribute__((address_space(3)))
; __device__ __forceinline__ void bias_tile(f32x16& p0, f32x16& p1, const LAS float* cs) {
; #pragma unroll
;     for (int i = 0; i < 4; ++i) { const f32x4 a = *(const LAS f32x4*)(cs + 8 * i), b = *(const LAS f32x4*)(cs + 32 + 8 * i);
; #pragma unroll
;         for (int j = 0; j < 4; ++j) { p0[4 * i + j] = fmaf(p0[4 * i + j], C2, a[j]); p1[4 * i + j] = fmaf(p1[4 * i + j], C2, b[j]); } }
; }
; template <int KB>
; __device__ __forceinline__ void qkt(f32x16& p0, f32x16& p1, lptr K_lds, int r32, int hi, const bf16x8* qr) {
;     p0 = f32x16{}; p1 = f32x16{};
;     lptr kb[4];
; #pragma unroll
;     for (int dd = 0; dd < 4; ++dd) kb[dd] = K_lds + KB * SHM_K + KSWZ(r32, (dd * 16 + hi * 8) * 2);
; #pragma unroll
;     for (int d0 = 0; d0 < 8; ++d0) { lptr a = kb[d0 & 3] + (d0 >> 2) * 128;
;         bf16x8 b0 = *reinterpret_cast<const LAS bf16x8*>(a);
;         bf16x8 b1 = *reinterpret_cast<const LAS bf16x8*>(a + 32 * 256);
;         p0 = __builtin_amdgcn_mfma_f32_32x32x16_bf16(b0, qr[d0], p0, 0, 0, 0);
;         p1 = __builtin_amdgcn_mfma_f32_32x32x16_bf16(b1, qr[d0], p1, 0, 0, 0); }
; }
	v_lshlrev_b32_e32 v2, 4, v174
	s_movk_i32 s9, 0x70
	v_and_b32_e32 v3, 0x70, v2
	v_lshl_add_u32 v4, v219, 8, 0
	v_bitop3_b32 v2, v162, v2, s9 bitop3:0x78
	v_add_u32_e32 v187, v4, v2
	v_bitop3_b32 v2, v162, v3, 32 bitop3:0x36
	v_add_u32_e32 v185, v4, v2
	v_bitop3_b32 v2, v162, v3, 64 bitop3:0x36
	s_movk_i32 s9, 0x60
	v_add_u32_e32 v184, v4, v2
	v_bitop3_b32 v2, v162, v3, s9 bitop3:0x36
	v_add_u32_e32 v183, v4, v2
	v_and_b32_e32 v214, 16, v174
	v_lshlrev_b32_e32 v214, 3, v214
	v_xor_b32_e32 v187, v187, v214
	v_xor_b32_e32 v185, v185, v214
	v_xor_b32_e32 v184, v184, v214
	v_xor_b32_e32 v183, v183, v214
	v_xor_b32_e32 v210, 0x80, v187
	v_xor_b32_e32 v211, 0x80, v185
	v_xor_b32_e32 v212, 0x80, v184
	v_xor_b32_e32 v213, 0x80, v183
	ds_read_b128 v[2:5], v187 offset:32768
	ds_read_b128 v[6:9], v187 offset:40960
	s_waitcnt lgkmcnt(1)
	v_mfma_f32_32x32x16_bf16 v[18:33], v[2:5], v[142:145], 0
	ds_read_b128 v[52:55], v185 offset:32768
	ds_read_b128 v[56:59], v185 offset:40960
	v_lshl_add_u32 v51, s82, 8, v182
	s_or_b32 s9, s8, 63
	s_cmp_le_i32 s9, s80
	s_waitcnt lgkmcnt(2)
	v_mfma_f32_32x32x16_bf16 v[2:17], v[6:9], v[142:145], 0
	s_waitcnt lgkmcnt(1)
	v_mfma_f32_32x32x16_bf16 v[18:33], v[52:55], v[138:141], v[18:33]
	s_waitcnt lgkmcnt(0)
	v_mfma_f32_32x32x16_bf16 v[2:17], v[56:59], v[138:141], v[2:17]
	ds_read_b128 v[52:55], v184 offset:32768
	ds_read_b128 v[56:59], v184 offset:40960
	s_waitcnt lgkmcnt(1)
	v_mfma_f32_32x32x16_bf16 v[18:33], v[52:55], v[134:137], v[18:33]
	s_waitcnt lgkmcnt(0)
	v_mfma_f32_32x32x16_bf16 v[2:17], v[56:59], v[134:137], v[2:17]
	ds_read_b128 v[52:55], v183 offset:32768
	ds_read_b128 v[56:59], v183 offset:40960
	s_waitcnt lgkmcnt(1)
	v_mfma_f32_32x32x16_bf16 v[18:33], v[52:55], v[130:133], v[18:33]
	s_waitcnt lgkmcnt(0)
	v_mfma_f32_32x32x16_bf16 v[2:17], v[56:59], v[130:133], v[2:17]
	ds_read_b128 v[52:55], v210 offset:32768
	ds_read_b128 v[56:59], v210 offset:40960
	s_waitcnt lgkmcnt(1)
	v_mfma_f32_32x32x16_bf16 v[18:33], v[52:55], v[126:129], v[18:33]
	s_waitcnt lgkmcnt(0)
	v_mfma_f32_32x32x16_bf16 v[2:17], v[56:59], v[126:129], v[2:17]
	ds_read_b128 v[52:55], v211 offset:32768
	ds_read_b128 v[56:59], v211 offset:40960
	s_waitcnt lgkmcnt(1)
	v_mfma_f32_32x32x16_bf16 v[18:33], v[52:55], v[122:125], v[18:33]
	s_waitcnt lgkmcnt(0)
	v_mfma_f32_32x32x16_bf16 v[2:17], v[56:59], v[122:125], v[2:17]
	ds_read_b128 v[52:55], v212 offset:32768
	ds_read_b128 v[56:59], v212 offset:40960
	s_waitcnt lgkmcnt(1)
	v_mfma_f32_32x32x16_bf16 v[18:33], v[52:55], v[118:121], v[18:33]
	s_waitcnt lgkmcnt(0)
	v_mfma_f32_32x32x16_bf16 v[2:17], v[56:59], v[118:121], v[2:17]
	ds_read_b128 v[52:55], v213 offset:32768
	ds_read_b128 v[56:59], v213 offset:40960
	s_waitcnt lgkmcnt(1)
	v_mfma_f32_32x32x16_bf16 v[18:33], v[52:55], v[114:117], v[18:33]
	s_waitcnt lgkmcnt(0)
	v_mfma_f32_32x32x16_bf16 v[2:17], v[56:59], v[114:117], v[2:17]
	ds_read_b128 v[52:55], v51 offset:128
	ds_read_b128 v[56:59], v51
	ds_read_b128 v[60:63], v51 offset:32
	ds_read_b128 v[64:67], v51 offset:160
	ds_read_b128 v[68:71], v51 offset:64
	ds_read_b128 v[72:75], v51 offset:192
	ds_read_b128 v[76:79], v51 offset:96
	ds_read_b128 v[80:83], v51 offset:224
	s_waitcnt lgkmcnt(5)
	s_nop 0
	v_pk_fma_f32 v[24:25], v[24:25], s[2:3], v[62:63] op_sel_hi:[1,0,1]
	s_waitcnt lgkmcnt(3)
	v_pk_fma_f32 v[28:29], v[28:29], s[2:3], v[70:71] op_sel_hi:[1,0,1]
	v_pk_fma_f32 v[26:27], v[26:27], s[2:3], v[68:69] op_sel_hi:[1,0,1]
	s_waitcnt lgkmcnt(1)
	v_pk_fma_f32 v[32:33], v[32:33], s[2:3], v[78:79] op_sel_hi:[1,0,1]
	v_pk_fma_f32 v[30:31], v[30:31], s[2:3], v[76:77] op_sel_hi:[1,0,1]
	v_pk_fma_f32 v[22:23], v[22:23], s[2:3], v[60:61] op_sel_hi:[1,0,1]
	v_pk_fma_f32 v[20:21], v[20:21], s[2:3], v[58:59] op_sel_hi:[1,0,1]
	v_pk_fma_f32 v[18:19], v[18:19], s[2:3], v[56:57] op_sel_hi:[1,0,1]
	s_waitcnt lgkmcnt(0)
	v_pk_fma_f32 v[16:17], v[16:17], s[2:3], v[82:83] op_sel_hi:[1,0,1]
	v_pk_fma_f32 v[14:15], v[14:15], s[2:3], v[80:81] op_sel_hi:[1,0,1]
	v_pk_fma_f32 v[12:13], v[12:13], s[2:3], v[74:75] op_sel_hi:[1,0,1]
	v_pk_fma_f32 v[10:11], v[10:11], s[2:3], v[72:73] op_sel_hi:[1,0,1]
	v_pk_fma_f32 v[8:9], v[8:9], s[2:3], v[66:67] op_sel_hi:[1,0,1]
	v_pk_fma_f32 v[6:7], v[6:7], s[2:3], v[64:65] op_sel_hi:[1,0,1]
	v_pk_fma_f32 v[4:5], v[4:5], s[2:3], v[54:55] op_sel_hi:[1,0,1]
	v_pk_fma_f32 v[2:3], v[2:3], s[2:3], v[52:53] op_sel_hi:[1,0,1]
	s_cbranch_scc1 .LBB0_863
; __device__ __forceinline__ void mask_tile(f32x16& p0, f32x16& p1, int dq) {
;     const float NEG = -__builtin_inff();
; #pragma unroll
;     for (int r = 0; r < 16; ++r) { const int c = (r & 3) + 8 * (r >> 2);
;         if (dq - c < 0) p0[r] = NEG;
;         if (dq - c - 32 < 0) p1[r] = NEG; }
; }
	v_subrev_u32_e32 v51, s8, v180
	v_cmp_gt_i32_e64 s[68:69], 26, v51
	v_cmp_gt_i32_e64 s[70:71], 27, v51
	v_cmp_gt_i32_e64 s[66:67], 25, v51
	s_and_b64 s[68:69], s[70:71], s[68:69]
	v_cmp_gt_i32_e64 s[64:65], 24, v51
	s_and_b64 s[66:67], s[68:69], s[66:67]
	v_cmp_gt_i32_e64 s[62:63], 19, v51
	s_and_b64 s[64:65], s[66:67], s[64:65]
	v_cmp_gt_i32_e64 s[60:61], 18, v51
	s_and_b64 s[62:63], s[64:65], s[62:63]
	v_cmp_gt_i32_e64 s[58:59], 17, v51
	s_and_b64 s[60:61], s[62:63], s[60:61]
	v_cmp_gt_i32_e64 s[56:57], 16, v51
	s_and_b64 s[58:59], s[60:61], s[58:59]
	v_cmp_gt_i32_e64 s[54:55], 11, v51
	s_and_b64 s[56:57], s[58:59], s[56:57]
	v_cmp_gt_i32_e64 s[52:53], 10, v51
	s_and_b64 s[54:55], s[56:57], s[54:55]
	v_cmp_gt_i32_e64 s[50:51], 9, v51
	s_and_b64 s[52:53], s[54:55], s[52:53]
	v_cmp_gt_i32_e64 s[48:49], 8, v51
	s_and_b64 s[50:51], s[52:53], s[50:51]
	v_cmp_gt_i32_e64 s[46:47], 3, v51
	s_and_b64 s[48:49], s[50:51], s[48:49]
	v_cmp_gt_i32_e64 s[44:45], 2, v51
	s_and_b64 s[46:47], s[48:49], s[46:47]
	v_cmp_gt_i32_e64 s[42:43], 1, v51
	s_and_b64 s[44:45], s[46:47], s[44:45]
	v_cmp_gt_i32_e64 s[38:39], 0, v51
	s_and_b64 s[42:43], s[44:45], s[42:43]
	s_and_b64 s[38:39], s[42:43], s[38:39]
	v_cmp_gt_i32_e64 s[36:37], 58, v51
	v_cndmask_b32_e64 v18, v18, v206, s[38:39]
	v_cmp_gt_i32_e64 s[38:39], 59, v51
	v_cmp_gt_i32_e64 s[34:35], 57, v51
	s_and_b64 s[36:37], s[38:39], s[36:37]
	v_cmp_gt_i32_e64 s[30:31], 56, v51
	s_and_b64 s[34:35], s[36:37], s[34:35]
	v_cmp_gt_i32_e64 s[28:29], 51, v51
	s_and_b64 s[30:31], s[34:35], s[30:31]
	v_cmp_gt_i32_e64 s[26:27], 50, v51
	s_and_b64 s[28:29], s[30:31], s[28:29]
	v_cmp_gt_i32_e64 s[24:25], 49, v51
	s_and_b64 s[26:27], s[28:29], s[26:27]
	v_cmp_gt_i32_e64 s[22:23], 48, v51
	s_and_b64 s[24:25], s[26:27], s[24:25]
	v_cmp_gt_i32_e64 s[20:21], 43, v51
	s_and_b64 s[22:23], s[24:25], s[22:23]
	v_cmp_gt_i32_e64 s[18:19], 42, v51
	s_and_b64 s[20:21], s[22:23], s[20:21]
	v_cmp_gt_i32_e64 s[16:17], 41, v51
	s_and_b64 s[18:19], s[20:21], s[18:19]
	v_cmp_gt_i32_e64 s[14:15], 40, v51
	s_and_b64 s[16:17], s[18:19], s[16:17]
	v_cmp_gt_i32_e64 s[12:13], 35, v51
	s_and_b64 s[14:15], s[16:17], s[14:15]
	v_cmp_gt_i32_e64 s[10:11], 34, v51
	s_and_b64 s[12:13], s[14:15], s[12:13]
	v_cmp_gt_i32_e64 s[8:9], 33, v51
	s_and_b64 s[10:11], s[12:13], s[10:11]
	v_cmp_gt_i32_e32 vcc, 32, v51
	s_and_b64 s[8:9], s[10:11], s[8:9]
	s_and_b64 vcc, s[8:9], vcc
	v_cndmask_b32_e64 v33, v33, v206, s[70:71]
	v_cndmask_b32_e64 v32, v32, v206, s[68:69]
	v_cndmask_b32_e64 v31, v31, v206, s[66:67]
	v_cndmask_b32_e64 v30, v30, v206, s[64:65]
	v_cndmask_b32_e64 v29, v29, v206, s[62:63]
	v_cndmask_b32_e64 v28, v28, v206, s[60:61]
	v_cndmask_b32_e64 v27, v27, v206, s[58:59]
	v_cndmask_b32_e64 v26, v26, v206, s[56:57]
	v_cndmask_b32_e64 v25, v25, v206, s[54:55]
	v_cndmask_b32_e64 v24, v24, v206, s[52:53]
	v_cndmask_b32_e64 v23, v23, v206, s[50:51]
	v_cndmask_b32_e64 v22, v22, v206, s[48:49]
	v_cndmask_b32_e64 v21, v21, v206, s[46:47]
	v_cndmask_b32_e64 v20, v20, v206, s[44:45]
	v_cndmask_b32_e64 v19, v19, v206, s[42:43]
	v_cndmask_b32_e64 v17, v17, v206, s[38:39]
	v_cndmask_b32_e64 v16, v16, v206, s[36:37]
	v_cndmask_b32_e64 v15, v15, v206, s[34:35]
	v_cndmask_b32_e64 v14, v14, v206, s[30:31]
	v_cndmask_b32_e64 v13, v13, v206, s[28:29]
	v_cndmask_b32_e64 v12, v12, v206, s[26:27]
	v_cndmask_b32_e64 v11, v11, v206, s[24:25]
	v_cndmask_b32_e64 v10, v10, v206, s[22:23]
	v_cndmask_b32_e64 v9, v9, v206, s[20:21]
	v_cndmask_b32_e64 v8, v8, v206, s[18:19]
	v_cndmask_b32_e64 v7, v7, v206, s[16:17]
	v_cndmask_b32_e64 v6, v6, v206, s[14:15]
	v_cndmask_b32_e64 v5, v5, v206, s[12:13]
	v_cndmask_b32_e64 v4, v4, v206, s[10:11]
	v_cndmask_b32_e64 v3, v3, v206, s[8:9]
	v_cndmask_b32_e32 v2, v2, v206, vcc

; #define LAS __attribute__((address_space(3)))
; __device__ __forceinline__ void finishSM(f32x16& p0, f32x16& p1, float alpha, float& l_reg, bf16x8& pa0, bf16x8& pa1, bf16x8& pa2, bf16x8& pa3) {
; #pragma unroll
;     for (int r = 0; r < 16; ++r) p1[r] = __builtin_amdgcn_exp2f(p1[r]);
;     float ps = 0;
; #pragma unroll
;     for (int r = 0; r < 16; ++r) ps += p0[r];
; #pragma unroll
;     for (int r = 0; r < 16; ++r) ps += p1[r];
;     { auto rr = __builtin_amdgcn_permlane32_swap(__float_as_uint(ps), __float_as_uint(ps), false, false);
;       ps = __uint_as_float(rr[0]) + __uint_as_float(rr[1]); }
;     l_reg = l_reg * alpha + ps;
;     ...
;     PK4(p0, 0, pa0); PK4(p0, 8, pa1); PK4(p1, 0, pa2); PK4(p1, 8, pa3);
; template <int KB>
; __device__ __forceinline__ void qkt(f32x16& p0, f32x16& p1, lptr K_lds, int r32, int hi, const bf16x8* qr) {
;     p0 = f32x16{}; p1 = f32x16{};
;     lptr kb[4];
; #pragma unroll
;     for (int dd = 0; dd < 4; ++dd) kb[dd] = K_lds + KB * SHM_K + KSWZ(r32, (dd * 16 + hi * 8) * 2);
; #pragma unroll
;     for (int d0 = 0; d0 < 8; ++d0) { lptr a = kb[d0 & 3] + (d0 >> 2) * 128;
;         bf16x8 b0 = *reinterpret_cast<const LAS bf16x8*>(a);
;         bf16x8 b1 = *reinterpret_cast<const LAS bf16x8*>(a + 32 * 256);
;         p0 = __builtin_amdgcn_mfma_f32_32x32x16_bf16(b0, qr[d0], p0, 0, 0, 0);
;         p1 = __builtin_amdgcn_mfma_f32_32x32x16_bf16(b1, qr[d0], p1, 0, 0, 0); }
; }
.LBB0_865:
	ds_read_b128 v[82:85], v187 offset:49152
	ds_read_b128 v[86:89], v187 offset:57344
	ds_read_b128 v[236:239], v185 offset:49152
	ds_read_b128 v[240:243], v185 offset:57344
	s_waitcnt lgkmcnt(3)
	v_mfma_f32_32x32x16_bf16 v[98:113], v[82:85], v[142:145], 0
	v_exp_f32_e32 v80, v80
	v_exp_f32_e32 v1, v1
	v_exp_f32_e32 v78, v78
	s_waitcnt lgkmcnt(2)
	v_mfma_f32_32x32x16_bf16 v[82:97], v[86:89], v[142:145], 0
	v_exp_f32_e32 v79, v79
	v_exp_f32_e32 v76, v76
	v_exp_f32_e32 v77, v77
	s_waitcnt lgkmcnt(0)
	v_mfma_f32_32x32x16_bf16 v[82:97], v[240:243], v[138:141], v[82:97]
	v_exp_f32_e32 v81, v74
	v_exp_f32_e32 v146, v75
	v_exp_f32_e32 v226, v72
	v_mfma_f32_32x32x16_bf16 v[98:113], v[236:239], v[138:141], v[98:113]
	v_exp_f32_e32 v233, v66
	v_add_f32_e32 v66, 0, v160
	v_add_f32_e32 v66, v227, v66
	v_add_f32_e32 v66, v158, v66
	v_add_f32_e32 v66, v161, v66
	ds_read_b128 v[236:239], v184 offset:49152
	ds_read_b128 v[240:243], v184 offset:57344
	s_waitcnt lgkmcnt(0)
	v_mfma_f32_32x32x16_bf16 v[82:97], v[240:243], v[134:137], v[82:97]
	v_add_f32_e32 v66, v157, v66
	v_add_f32_e32 v66, v159, v66
	v_add_f32_e32 v66, v155, v66
	v_add_f32_e32 v66, v156, v66
	v_add_f32_e32 v66, v152, v66
	v_add_f32_e32 v66, v154, v66
	v_mfma_f32_32x32x16_bf16 v[98:113], v[236:239], v[134:137], v[98:113]
	v_add_f32_e32 v66, v151, v66
	v_add_f32_e32 v66, v153, v66
	v_add_f32_e32 v66, v148, v66
	v_add_f32_e32 v66, v150, v66
	v_add_f32_e32 v66, v147, v66
	v_add_f32_e32 v66, v149, v66
	ds_read_b128 v[236:239], v183 offset:49152
	ds_read_b128 v[240:243], v183 offset:57344
	s_waitcnt lgkmcnt(0)
	v_mfma_f32_32x32x16_bf16 v[82:97], v[240:243], v[130:133], v[82:97]
	v_add_f32_e32 v66, v80, v66
	v_add_f32_e32 v66, v1, v66
	v_add_f32_e32 v66, v78, v66
	v_add_f32_e32 v66, v79, v66
	v_add_f32_e32 v66, v76, v66
	v_mfma_f32_32x32x16_bf16 v[98:113], v[236:239], v[130:133], v[98:113]
	v_exp_f32_e32 v228, v73
	v_add_f32_e32 v66, v77, v66
	v_exp_f32_e32 v229, v70
	v_add_f32_e32 v66, v81, v66
	ds_read_b128 v[236:239], v210 offset:49152
	ds_read_b128 v[240:243], v210 offset:57344
	s_waitcnt lgkmcnt(0)
	v_mfma_f32_32x32x16_bf16 v[82:97], v[240:243], v[126:129], v[82:97]
	v_exp_f32_e32 v230, v71
	v_add_f32_e32 v66, v146, v66
	v_exp_f32_e32 v231, v68
	v_add_f32_e32 v66, v226, v66
	v_mfma_f32_32x32x16_bf16 v[98:113], v[236:239], v[126:129], v[98:113]
	v_exp_f32_e32 v232, v69
	v_add_f32_e32 v66, v228, v66
	v_add_f32_e32 v66, v229, v66
	v_exp_f32_e32 v234, v67
	ds_read_b128 v[236:239], v211 offset:49152
	ds_read_b128 v[240:243], v211 offset:57344
	s_waitcnt lgkmcnt(0)
	v_mfma_f32_32x32x16_bf16 v[82:97], v[240:243], v[122:125], v[82:97]
	v_add_f32_e32 v66, v230, v66
	v_add_f32_e32 v66, v231, v66
	v_add_f32_e32 v66, v232, v66
	v_add_f32_e32 v66, v233, v66
	v_add_f32_e32 v224, v234, v66
	v_mov_b32_e32 v225, v224
	v_mfma_f32_32x32x16_bf16 v[98:113], v[236:239], v[122:125], v[98:113]
	v_cvt_pk_bf16_f32 v66, v160, v227
	v_cvt_pk_bf16_f32 v67, v158, v161
	v_cvt_pk_bf16_f32 v68, v157, v159
	v_cvt_pk_bf16_f32 v69, v155, v156
	v_cvt_pk_bf16_f32 v70, v152, v154
	v_cvt_pk_bf16_f32 v71, v151, v153
	ds_read_b128 v[236:239], v212 offset:49152
	ds_read_b128 v[240:243], v212 offset:57344
	s_waitcnt lgkmcnt(0)
	v_mfma_f32_32x32x16_bf16 v[82:97], v[240:243], v[118:121], v[82:97]
	v_cvt_pk_bf16_f32 v72, v148, v150
	v_cvt_pk_bf16_f32 v73, v147, v149
	v_cvt_pk_bf16_f32 v74, v80, v1
	v_cvt_pk_bf16_f32 v75, v78, v79
	v_cvt_pk_bf16_f32 v76, v76, v77
	v_cvt_pk_bf16_f32 v77, v81, v146
	v_mfma_f32_32x32x16_bf16 v[98:113], v[236:239], v[118:121], v[98:113]
	v_cvt_pk_bf16_f32 v78, v226, v228
	v_cvt_pk_bf16_f32 v79, v229, v230
	v_cvt_pk_bf16_f32 v80, v231, v232
	v_cvt_pk_bf16_f32 v81, v233, v234
	s_nop 1
	v_permlane32_swap_b32_e32 v224, v225
	ds_read_b128 v[236:239], v213 offset:49152
	ds_read_b128 v[240:243], v213 offset:57344
	s_waitcnt lgkmcnt(0)
	v_mfma_f32_32x32x16_bf16 v[82:97], v[240:243], v[114:117], v[82:97]
	v_permlane32_swap_b32_e32 v66, v68
	v_permlane32_swap_b32_e32 v67, v69
	v_permlane32_swap_b32_e32 v70, v72
	v_permlane32_swap_b32_e32 v71, v73
	v_permlane32_swap_b32_e32 v74, v76
	v_permlane32_swap_b32_e32 v75, v77
	v_mfma_f32_32x32x16_bf16 v[98:113], v[236:239], v[114:117], v[98:113]
	v_permlane32_swap_b32_e32 v78, v80
	v_permlane32_swap_b32_e32 v79, v81
	v_add_u32_e32 v227, s89, v186
	v_add_u32_e32 v146, 1, v227
	v_add_u32_e32 v148, 33, v227
	v_ashrrev_i32_e32 v147, 31, v146
	v_ashrrev_i32_e32 v149, 31, v148
	v_lshlrev_b64 v[154:155], 8, v[146:147]
	v_lshlrev_b64 v[156:157], 8, v[148:149]
	v_lshl_add_u64 v[146:147], v[176:177], 0, v[154:155]
	v_lshl_add_u64 v[150:151], v[176:177], 0, v[156:157]
	v_lshl_add_u64 v[154:155], v[178:179], 0, v[154:155]
	v_lshl_add_u64 v[158:159], v[178:179], 0, v[156:157]
	global_load_dwordx4 v[146:149], v[146:147], off
	s_nop 0
	global_load_dwordx4 v[150:153], v[150:151], off
	s_nop 0
	global_load_dwordx4 v[154:157], v[154:155], off
	s_nop 0
	global_load_dwordx4 v[158:161], v[158:159], off
	ds_read_b64_tr_b16 v[228:229], v181 offset:0
	ds_read_b64_tr_b16 v[230:231], v181 offset:0x800
	ds_read_b64_tr_b16 v[232:233], v181 offset:0x1000
	ds_read_b64_tr_b16 v[234:235], v181 offset:0x1800
	ds_read_b64_tr_b16 v[236:237], v181 offset:0x2000
	ds_read_b64_tr_b16 v[238:239], v181 offset:0x2800
	ds_read_b64_tr_b16 v[240:241], v181 offset:0x3000
	ds_read_b64_tr_b16 v[242:243], v181 offset:0x3800
	s_waitcnt lgkmcnt(0)
; #define LAS __attribute__((address_space(3)))
; __device__ __forceinline__ void bias_tile(f32x16& p0, f32x16& p1, const LAS float* cs) {
; #pragma unroll
;     for (int i = 0; i < 4; ++i) { const f32x4 a = *(const LAS f32x4*)(cs + 8 * i), b = *(const LAS f32x4*)(cs + 32 + 8 * i);
; #pragma unroll
;         for (int j = 0; j < 4; ++j) { p0[4 * i + j] = fmaf(p0[4 * i + j], C2, a[j]); p1[4 * i + j] = fmaf(p1[4 * i + j], C2, b[j]); } }
; }
; template <int VB>
; __device__ __forceinline__ void pv_tile(f32x16* o, int vb0, bf16x8 pa0, bf16x8 pa1, bf16x8 pa2, bf16x8 pa3) {
;     ...
;     PV_D0(0); PV_D0(1); PV_D0(2); PV_D0(3);
	s_nop 0
	v_mfma_f32_32x32x16_bf16 v[50:65], v[66:69], v[228:231], v[50:65]
	ds_read_b64_tr_b16 v[228:229], v181 offset:0x200
	ds_read_b64_tr_b16 v[230:231], v181 offset:0xa00
	v_mfma_f32_32x32x16_bf16 v[50:65], v[70:73], v[232:235], v[50:65]
	ds_read_b64_tr_b16 v[232:233], v181 offset:0x1200
	ds_read_b64_tr_b16 v[234:235], v181 offset:0x1a00
	v_mfma_f32_32x32x16_bf16 v[50:65], v[74:77], v[236:239], v[50:65]
	ds_read_b64_tr_b16 v[236:237], v181 offset:0x2200
	ds_read_b64_tr_b16 v[238:239], v181 offset:0x2a00
	v_mfma_f32_32x32x16_bf16 v[50:65], v[78:81], v[240:243], v[50:65]
	ds_read_b64_tr_b16 v[240:241], v181 offset:0x3200
	ds_read_b64_tr_b16 v[242:243], v181 offset:0x3a00
	s_waitcnt lgkmcnt(0)
	v_mfma_f32_32x32x16_bf16 v[34:49], v[66:69], v[228:231], v[34:49]
	ds_read_b64_tr_b16 v[228:229], v181 offset:0x400
	ds_read_b64_tr_b16 v[230:231], v181 offset:0xc00
	v_mfma_f32_32x32x16_bf16 v[34:49], v[70:73], v[232:235], v[34:49]
	ds_read_b64_tr_b16 v[232:233], v181 offset:0x1400
	ds_read_b64_tr_b16 v[234:235], v181 offset:0x1c00
	v_mfma_f32_32x32x16_bf16 v[34:49], v[74:77], v[236:239], v[34:49]
	ds_read_b64_tr_b16 v[236:237], v181 offset:0x2400
	ds_read_b64_tr_b16 v[238:239], v181 offset:0x2c00
	v_mfma_f32_32x32x16_bf16 v[34:49], v[78:81], v[240:243], v[34:49]
	ds_read_b64_tr_b16 v[240:241], v181 offset:0x3400
	ds_read_b64_tr_b16 v[242:243], v181 offset:0x3c00
	s_waitcnt lgkmcnt(0)
	v_mfma_f32_32x32x16_bf16 v[18:33], v[66:69], v[228:231], v[18:33]
	ds_read_b64_tr_b16 v[228:229], v181 offset:0x600
	ds_read_b64_tr_b16 v[230:231], v181 offset:0xe00
	v_mfma_f32_32x32x16_bf16 v[18:33], v[70:73], v[232:235], v[18:33]
	ds_read_b64_tr_b16 v[232:233], v181 offset:0x1600
	ds_read_b64_tr_b16 v[234:235], v181 offset:0x1e00
	v_mfma_f32_32x32x16_bf16 v[18:33], v[74:77], v[236:239], v[18:33]
	ds_read_b64_tr_b16 v[236:237], v181 offset:0x2600
	ds_read_b64_tr_b16 v[238:239], v181 offset:0x2e00
	v_mfma_f32_32x32x16_bf16 v[18:33], v[78:81], v[240:243], v[18:33]
	ds_read_b64_tr_b16 v[240:241], v181 offset:0x3600
	ds_read_b64_tr_b16 v[242:243], v181 offset:0x3e00
	s_waitcnt lgkmcnt(0)
	v_mfma_f32_32x32x16_bf16 v[2:17], v[66:69], v[228:231], v[2:17]
	s_cmp_le_i32 s89, s80
	v_mfma_f32_32x32x16_bf16 v[2:17], v[70:73], v[232:235], v[2:17]
	v_mfma_f32_32x32x16_bf16 v[2:17], v[74:77], v[236:239], v[2:17]
	v_mfma_f32_32x32x16_bf16 v[2:17], v[78:81], v[240:243], v[2:17]
	ds_read_b128 v[228:231], v223 offset:128
	ds_read_b128 v[78:81], v223
	ds_read_b128 v[70:73], v223 offset:32
	ds_read_b128 v[232:235], v223 offset:160
	ds_read_b128 v[74:77], v223 offset:64
	ds_read_b128 v[236:239], v223 offset:192
	ds_read_b128 v[240:243], v223 offset:96
	ds_read_b128 v[244:247], v223 offset:224
	s_waitcnt lgkmcnt(6)
	v_pk_fma_f32 v[100:101], v[100:101], s[2:3], v[80:81] op_sel_hi:[1,0,1]
	s_waitcnt lgkmcnt(3)
	v_pk_fma_f32 v[68:69], v[106:107], s[2:3], v[74:75] op_sel_hi:[1,0,1]
	v_pk_fma_f32 v[74:75], v[102:103], s[2:3], v[70:71] op_sel_hi:[1,0,1]
	s_waitcnt lgkmcnt(1)
	v_pk_fma_f32 v[66:67], v[110:111], s[2:3], v[240:241] op_sel_hi:[1,0,1]
	v_pk_fma_f32 v[70:71], v[112:113], s[2:3], v[242:243] op_sel_hi:[1,0,1]
	v_pk_fma_f32 v[76:77], v[108:109], s[2:3], v[76:77] op_sel_hi:[1,0,1]
	v_pk_fma_f32 v[102:103], v[104:105], s[2:3], v[72:73] op_sel_hi:[1,0,1]
	v_pk_fma_f32 v[98:99], v[98:99], s[2:3], v[78:79] op_sel_hi:[1,0,1]
	s_waitcnt lgkmcnt(0)
	v_pk_fma_f32 v[72:73], v[94:95], s[2:3], v[244:245] op_sel_hi:[1,0,1]
	v_pk_fma_f32 v[78:79], v[90:91], s[2:3], v[236:237] op_sel_hi:[1,0,1]
	v_pk_fma_f32 v[86:87], v[86:87], s[2:3], v[232:233] op_sel_hi:[1,0,1]
	v_pk_fma_f32 v[80:81], v[96:97], s[2:3], v[246:247] op_sel_hi:[1,0,1]
	v_pk_fma_f32 v[90:91], v[92:93], s[2:3], v[238:239] op_sel_hi:[1,0,1]
	v_pk_fma_f32 v[88:89], v[88:89], s[2:3], v[234:235] op_sel_hi:[1,0,1]
	v_pk_fma_f32 v[84:85], v[84:85], s[2:3], v[230:231] op_sel_hi:[1,0,1]
	v_pk_fma_f32 v[82:83], v[82:83], s[2:3], v[228:229] op_sel_hi:[1,0,1]
	s_cbranch_scc1 .LBB0_867
; __device__ __forceinline__ void mask_tile(f32x16& p0, f32x16& p1, int dq) {
;     const float NEG = -__builtin_inff();
; #pragma unroll
;     for (int r = 0; r < 16; ++r) { const int c = (r & 3) + 8 * (r >> 2);
;         if (dq - c < 0) p0[r] = NEG;
;         if (dq - c - 32 < 0) p1[r] = NEG; }
; }
	v_add_u32_e32 v1, 64, v222
	v_cmp_gt_i32_e64 s[70:71], 26, v1
	v_cmp_gt_i32_e64 s[72:73], 27, v1
	v_cmp_gt_i32_e64 s[68:69], 25, v1
	s_and_b64 s[70:71], s[72:73], s[70:71]
	v_cmp_gt_i32_e64 s[66:67], 24, v1
	s_and_b64 s[68:69], s[70:71], s[68:69]
	v_cmp_gt_i32_e64 s[64:65], 19, v1
	s_and_b64 s[66:67], s[68:69], s[66:67]
	v_cmp_gt_i32_e64 s[62:63], 18, v1
	s_and_b64 s[64:65], s[66:67], s[64:65]
	v_cmp_gt_i32_e64 s[60:61], 17, v1
	s_and_b64 s[62:63], s[64:65], s[62:63]
	v_cmp_gt_i32_e64 s[58:59], 16, v1
	s_and_b64 s[60:61], s[62:63], s[60:61]
	v_cmp_gt_i32_e64 s[56:57], 11, v1
	s_and_b64 s[58:59], s[60:61], s[58:59]
	v_cmp_gt_i32_e64 s[54:55], 10, v1
	s_and_b64 s[56:57], s[58:59], s[56:57]
	v_cmp_gt_i32_e64 s[52:53], 9, v1
	s_and_b64 s[54:55], s[56:57], s[54:55]
	v_cmp_gt_i32_e64 s[50:51], 8, v1
	s_and_b64 s[52:53], s[54:55], s[52:53]
	v_cmp_gt_i32_e64 s[48:49], 3, v1
	s_and_b64 s[50:51], s[52:53], s[50:51]
	v_cmp_gt_i32_e64 s[46:47], 2, v1
	s_and_b64 s[48:49], s[50:51], s[48:49]
	v_cmp_gt_i32_e64 s[44:45], 1, v1
	s_and_b64 s[46:47], s[48:49], s[46:47]
	v_cmp_gt_i32_e64 s[42:43], 0, v1
	s_and_b64 s[44:45], s[46:47], s[44:45]
	s_and_b64 s[42:43], s[44:45], s[42:43]
	v_cmp_gt_i32_e64 s[38:39], 58, v1
	v_cndmask_b32_e64 v98, v98, v206, s[42:43]
	v_cmp_gt_i32_e64 s[42:43], 59, v1
	v_cmp_gt_i32_e64 s[36:37], 57, v1
	s_and_b64 s[38:39], s[42:43], s[38:39]
	v_cmp_gt_i32_e64 s[34:35], 56, v1
	s_and_b64 s[36:37], s[38:39], s[36:37]
	v_cmp_gt_i32_e64 s[30:31], 51, v1
	s_and_b64 s[34:35], s[36:37], s[34:35]
	v_cmp_gt_i32_e64 s[28:29], 50, v1
	s_and_b64 s[30:31], s[34:35], s[30:31]
	v_cmp_gt_i32_e64 s[26:27], 49, v1
	s_and_b64 s[28:29], s[30:31], s[28:29]
	v_cmp_gt_i32_e64 s[24:25], 48, v1
	s_and_b64 s[26:27], s[28:29], s[26:27]
	v_cmp_gt_i32_e64 s[22:23], 43, v1
	s_and_b64 s[24:25], s[26:27], s[24:25]
	v_cmp_gt_i32_e64 s[20:21], 42, v1
	s_and_b64 s[22:23], s[24:25], s[22:23]
	v_cmp_gt_i32_e64 s[18:19], 41, v1
	s_and_b64 s[20:21], s[22:23], s[20:21]
	v_cmp_gt_i32_e64 s[16:17], 40, v1
	s_and_b64 s[18:19], s[20:21], s[18:19]
	v_cmp_gt_i32_e64 s[14:15], 35, v1
	s_and_b64 s[16:17], s[18:19], s[16:17]
	v_cmp_gt_i32_e64 s[12:13], 34, v1
	s_and_b64 s[14:15], s[16:17], s[14:15]
	v_cmp_gt_i32_e64 s[10:11], 33, v1
	s_and_b64 s[12:13], s[14:15], s[12:13]
	v_cmp_gt_i32_e32 vcc, 32, v1
	s_and_b64 s[10:11], s[12:13], s[10:11]
	s_and_b64 vcc, s[10:11], vcc
	v_cndmask_b32_e64 v71, v71, v206, s[72:73]
	v_cndmask_b32_e64 v70, v70, v206, s[70:71]
	v_cndmask_b32_e64 v67, v67, v206, s[68:69]
	v_cndmask_b32_e64 v66, v66, v206, s[66:67]
	v_cndmask_b32_e64 v77, v77, v206, s[64:65]
	v_cndmask_b32_e64 v76, v76, v206, s[62:63]
	v_cndmask_b32_e64 v69, v69, v206, s[60:61]
	v_cndmask_b32_e64 v68, v68, v206, s[58:59]
	v_cndmask_b32_e64 v103, v103, v206, s[56:57]
	v_cndmask_b32_e64 v102, v102, v206, s[54:55]
	v_cndmask_b32_e64 v75, v75, v206, s[52:53]
	v_cndmask_b32_e64 v74, v74, v206, s[50:51]
	v_cndmask_b32_e64 v101, v101, v206, s[48:49]
	v_cndmask_b32_e64 v100, v100, v206, s[46:47]
	v_cndmask_b32_e64 v99, v99, v206, s[44:45]
	v_cndmask_b32_e64 v81, v81, v206, s[42:43]
	v_cndmask_b32_e64 v80, v80, v206, s[38:39]
	v_cndmask_b32_e64 v73, v73, v206, s[36:37]
	v_cndmask_b32_e64 v72, v72, v206, s[34:35]
	v_cndmask_b32_e64 v91, v91, v206, s[30:31]
	v_cndmask_b32_e64 v90, v90, v206, s[28:29]
	v_cndmask_b32_e64 v79, v79, v206, s[26:27]
	v_cndmask_b32_e64 v78, v78, v206, s[24:25]
	v_cndmask_b32_e64 v89, v89, v206, s[22:23]
	v_cndmask_b32_e64 v88, v88, v206, s[20:21]
	v_cndmask_b32_e64 v87, v87, v206, s[18:19]
	v_cndmask_b32_e64 v86, v86, v206, s[16:17]
	v_cndmask_b32_e64 v85, v85, v206, s[14:15]
	v_cndmask_b32_e64 v84, v84, v206, s[12:13]
	v_cndmask_b32_e64 v83, v83, v206, s[10:11]
	v_cndmask_b32_e32 v82, v82, v206, vcc

; #define LAS __attribute__((address_space(3)))
; __device__ __forceinline__ void partialSM(f32x16& p0, f32x16& p1, float& m_reg, float& alpha) {
;     ...
; #pragma unroll
;     for (int r = 0; r < 16; ++r) p0[r] = p0[r] - mn;
; #pragma unroll
;     for (int r = 0; r < 16; ++r) p1[r] = p1[r] - mn;
; #pragma unroll
;     for (int r = 0; r < 16; ++r) p0[r] = __builtin_amdgcn_exp2f(p0[r]);
; }
; __device__ __forceinline__ void finishSM(f32x16& p0, f32x16& p1, float alpha, float& l_reg, bf16x8& pa0, bf16x8& pa1, bf16x8& pa2, bf16x8& pa3) {
; #pragma unroll
;     for (int r = 0; r < 16; ++r) p1[r] = __builtin_amdgcn_exp2f(p1[r]);
;     float ps = 0;
; #pragma unroll
;     for (int r = 0; r < 16; ++r) ps += p0[r];
; #pragma unroll
;     for (int r = 0; r < 16; ++r) ps += p1[r];
;     { auto rr = __builtin_amdgcn_permlane32_swap(__float_as_uint(ps), __float_as_uint(ps), false, false);
;       ps = __uint_as_float(rr[0]) + __uint_as_float(rr[1]); }
;     l_reg = l_reg * alpha + ps;
;     ...
;     PK4(p0, 0, pa0); PK4(p0, 8, pa1); PK4(p1, 0, pa2); PK4(p1, 8, pa3);
; template <int KB>
; __device__ __forceinline__ void qkt(f32x16& p0, f32x16& p1, lptr K_lds, int r32, int hi, const bf16x8* qr) {
;     p0 = f32x16{}; p1 = f32x16{};
;     lptr kb[4];
; #pragma unroll
;     for (int dd = 0; dd < 4; ++dd) kb[dd] = K_lds + KB * SHM_K + KSWZ(r32, (dd * 16 + hi * 8) * 2);
; #pragma unroll
;     for (int d0 = 0; d0 < 8; ++d0) { lptr a = kb[d0 & 3] + (d0 >> 2) * 128;
;         bf16x8 b0 = *reinterpret_cast<const LAS bf16x8*>(a);
;         bf16x8 b1 = *reinterpret_cast<const LAS bf16x8*>(a + 32 * 256);
;         p0 = __builtin_amdgcn_mfma_f32_32x32x16_bf16(b0, qr[d0], p0, 0, 0, 0);
;         p1 = __builtin_amdgcn_mfma_f32_32x32x16_bf16(b1, qr[d0], p1, 0, 0, 0); }
; }
.LBB0_871:
	v_cndmask_b32_e64 v1, v1, v220, s[10:11]
	v_sub_f32_e32 v92, v98, v1
	v_sub_f32_e32 v93, v99, v1
	v_sub_f32_e32 v94, v100, v1
	v_sub_f32_e32 v95, v101, v1
	v_sub_f32_e32 v74, v74, v1
	v_sub_f32_e32 v75, v75, v1
	v_sub_f32_e32 v96, v102, v1
	v_sub_f32_e32 v97, v103, v1
	v_sub_f32_e32 v68, v68, v1
	v_sub_f32_e32 v69, v69, v1
	v_sub_f32_e32 v76, v76, v1
	v_sub_f32_e32 v77, v77, v1
	v_sub_f32_e32 v66, v66, v1
	v_sub_f32_e32 v67, v67, v1
	v_sub_f32_e32 v70, v70, v1
	v_sub_f32_e32 v71, v71, v1
	v_exp_f32_e32 v98, v92
	v_exp_f32_e32 v113, v93
	v_exp_f32_e32 v99, v94
	v_exp_f32_e32 v112, v95
	v_exp_f32_e32 v100, v74
	v_exp_f32_e32 v111, v75
	v_exp_f32_e32 v101, v96
	v_exp_f32_e32 v110, v97
	v_exp_f32_e32 v102, v68
	v_exp_f32_e32 v109, v69
	v_exp_f32_e32 v103, v76
	v_exp_f32_e32 v108, v77
	v_exp_f32_e32 v104, v66
	v_exp_f32_e32 v107, v67
	v_exp_f32_e32 v105, v70
	v_exp_f32_e32 v106, v71
	v_sub_f32_e32 v220, v82, v1
	v_sub_f32_e32 v236, v83, v1
	v_sub_f32_e32 v237, v84, v1
	v_sub_f32_e32 v238, v85, v1
	v_sub_f32_e32 v239, v86, v1
	v_sub_f32_e32 v240, v87, v1
	v_sub_f32_e32 v241, v88, v1
	v_sub_f32_e32 v242, v89, v1
	v_sub_f32_e32 v243, v78, v1
	v_sub_f32_e32 v244, v79, v1
	v_sub_f32_e32 v245, v90, v1
	v_sub_f32_e32 v246, v91, v1
	v_sub_f32_e32 v247, v72, v1
	v_sub_f32_e32 v248, v73, v1
	v_sub_f32_e32 v249, v80, v1
	v_sub_f32_e32 v250, v81, v1
	s_waitcnt lgkmcnt(0)
	s_barrier
	ds_read_b128 v[66:69], v187 offset:32768
	ds_read_b128 v[70:73], v187 offset:40960
	ds_read_b128 v[146:149], v185 offset:32768
	ds_read_b128 v[150:153], v185 offset:40960
	s_waitcnt lgkmcnt(3)
	v_mfma_f32_32x32x16_bf16 v[82:97], v[66:69], v[142:145], 0
	v_exp_f32_e32 v220, v220
	v_add_f32_e32 v228, 0, v98
	v_add_f32_e32 v228, v113, v228
	v_add_f32_e32 v228, v99, v228
	v_add_f32_e32 v228, v112, v228
	s_waitcnt lgkmcnt(2)
	v_mfma_f32_32x32x16_bf16 v[66:81], v[70:73], v[142:145], 0
	v_add_f32_e32 v228, v100, v228
	v_add_f32_e32 v228, v111, v228
	v_add_f32_e32 v228, v101, v228
	v_add_f32_e32 v228, v110, v228
	v_add_f32_e32 v228, v102, v228
	v_add_f32_e32 v228, v109, v228
	s_waitcnt lgkmcnt(1)
	v_mfma_f32_32x32x16_bf16 v[82:97], v[146:149], v[138:141], v[82:97]
	v_add_f32_e32 v228, v103, v228
	v_add_f32_e32 v228, v108, v228
	v_add_f32_e32 v228, v104, v228
	v_exp_f32_e32 v230, v236
	v_add_f32_e32 v228, v107, v228
	s_waitcnt lgkmcnt(0)
	v_mfma_f32_32x32x16_bf16 v[66:81], v[150:153], v[138:141], v[66:81]
	v_exp_f32_e32 v231, v237
	v_add_f32_e32 v228, v105, v228
	v_exp_f32_e32 v232, v238
	v_add_f32_e32 v228, v106, v228
	ds_read_b128 v[146:149], v184 offset:32768
	ds_read_b128 v[150:153], v184 offset:40960
	s_waitcnt lgkmcnt(1)
	v_mfma_f32_32x32x16_bf16 v[82:97], v[146:149], v[134:137], v[82:97]
	v_exp_f32_e32 v233, v239
	v_add_f32_e32 v228, v220, v228
	v_exp_f32_e32 v234, v240
	v_add_f32_e32 v228, v230, v228
	s_waitcnt lgkmcnt(0)
	v_mfma_f32_32x32x16_bf16 v[66:81], v[150:153], v[134:137], v[66:81]
	v_exp_f32_e32 v235, v241
	v_add_f32_e32 v228, v231, v228
	v_exp_f32_e32 v236, v242
	v_add_f32_e32 v228, v232, v228
	ds_read_b128 v[146:149], v183 offset:32768
	ds_read_b128 v[150:153], v183 offset:40960
	s_waitcnt lgkmcnt(1)
	v_mfma_f32_32x32x16_bf16 v[82:97], v[146:149], v[130:133], v[82:97]
	v_exp_f32_e32 v237, v243
	v_add_f32_e32 v228, v233, v228
	v_exp_f32_e32 v238, v244
	v_add_f32_e32 v228, v234, v228
	s_waitcnt lgkmcnt(0)
	v_mfma_f32_32x32x16_bf16 v[66:81], v[150:153], v[130:133], v[66:81]
	v_exp_f32_e32 v239, v245
	v_add_f32_e32 v228, v235, v228
	v_exp_f32_e32 v240, v246
	v_add_f32_e32 v228, v236, v228
	ds_read_b128 v[146:149], v210 offset:32768
	ds_read_b128 v[150:153], v210 offset:40960
	s_waitcnt lgkmcnt(1)
	v_mfma_f32_32x32x16_bf16 v[82:97], v[146:149], v[126:129], v[82:97]
	v_exp_f32_e32 v241, v247
	v_add_f32_e32 v228, v237, v228
	v_exp_f32_e32 v242, v248
	v_add_f32_e32 v228, v238, v228
	s_waitcnt lgkmcnt(0)
	v_mfma_f32_32x32x16_bf16 v[66:81], v[150:153], v[126:129], v[66:81]
	v_exp_f32_e32 v243, v249
	v_add_f32_e32 v228, v239, v228
	v_exp_f32_e32 v244, v250
	v_add_f32_e32 v228, v240, v228
	ds_read_b128 v[146:149], v211 offset:32768
	ds_read_b128 v[150:153], v211 offset:40960
	s_waitcnt lgkmcnt(1)
	v_mfma_f32_32x32x16_bf16 v[82:97], v[146:149], v[122:125], v[82:97]
	v_add_f32_e32 v228, v241, v228
	v_add_f32_e32 v228, v242, v228
	v_add_f32_e32 v228, v243, v228
	v_add_f32_e32 v228, v244, v228
	v_mov_b32_e32 v229, v228
	v_cvt_pk_bf16_f32 v98, v98, v113
	s_waitcnt lgkmcnt(0)
	v_mfma_f32_32x32x16_bf16 v[66:81], v[150:153], v[122:125], v[66:81]
	v_cvt_pk_bf16_f32 v99, v99, v112
	v_cvt_pk_bf16_f32 v100, v100, v111
	v_cvt_pk_bf16_f32 v101, v101, v110
	v_cvt_pk_bf16_f32 v102, v102, v109
	v_cvt_pk_bf16_f32 v103, v103, v108
	v_cvt_pk_bf16_f32 v104, v104, v107
	ds_read_b128 v[146:149], v212 offset:32768
	ds_read_b128 v[150:153], v212 offset:40960
	s_waitcnt lgkmcnt(1)
	v_mfma_f32_32x32x16_bf16 v[82:97], v[146:149], v[118:121], v[82:97]
	v_cvt_pk_bf16_f32 v105, v105, v106
	v_cvt_pk_bf16_f32 v106, v220, v230
	v_cvt_pk_bf16_f32 v107, v231, v232
	v_cvt_pk_bf16_f32 v108, v233, v234
	v_cvt_pk_bf16_f32 v109, v235, v236
	v_cvt_pk_bf16_f32 v110, v237, v238
	s_waitcnt lgkmcnt(0)
	v_mfma_f32_32x32x16_bf16 v[66:81], v[150:153], v[118:121], v[66:81]
	v_cvt_pk_bf16_f32 v111, v239, v240
	v_cvt_pk_bf16_f32 v112, v241, v242
	v_cvt_pk_bf16_f32 v113, v243, v244
	s_nop 1
	v_permlane32_swap_b32_e32 v228, v229
	v_permlane32_swap_b32_e32 v98, v100
	ds_read_b128 v[146:149], v213 offset:32768
	ds_read_b128 v[150:153], v213 offset:40960
	s_waitcnt lgkmcnt(1)
	v_mfma_f32_32x32x16_bf16 v[82:97], v[146:149], v[114:117], v[82:97]
	v_permlane32_swap_b32_e32 v99, v101
	v_permlane32_swap_b32_e32 v102, v104
	v_permlane32_swap_b32_e32 v103, v105
	v_permlane32_swap_b32_e32 v106, v108
	v_permlane32_swap_b32_e32 v107, v109
	v_permlane32_swap_b32_e32 v110, v112
	s_waitcnt lgkmcnt(0)
	v_mfma_f32_32x32x16_bf16 v[66:81], v[150:153], v[114:117], v[66:81]
	v_permlane32_swap_b32_e32 v111, v113
	s_add_i32 s10, s88, 1
	s_cmp_lt_i32 s10, s81
	s_cselect_b64 s[40:41], -1, 0
	s_cmp_ge_i32 s10, s81
	s_cbranch_scc1 .LBB0_873
	v_add_u32_e32 v146, 0x41, v227
	v_add_u32_e32 v148, 0x61, v227
	v_ashrrev_i32_e32 v147, 31, v146
	v_ashrrev_i32_e32 v149, 31, v148
	v_lshlrev_b64 v[154:155], 8, v[146:147]
	v_lshlrev_b64 v[156:157], 8, v[148:149]
	v_lshl_add_u64 v[146:147], v[176:177], 0, v[154:155]
	v_lshl_add_u64 v[150:151], v[176:177], 0, v[156:157]
	v_lshl_add_u64 v[154:155], v[178:179], 0, v[154:155]
	v_lshl_add_u64 v[158:159], v[178:179], 0, v[156:157]
	global_load_dwordx4 v[146:149], v[146:147], off
	s_nop 0
	global_load_dwordx4 v[150:153], v[150:151], off
	s_nop 0
	global_load_dwordx4 v[154:157], v[154:155], off
	s_nop 0
	global_load_dwordx4 v[158:161], v[158:159], off

; #define SBAR() __builtin_amdgcn_sched_barrier(0)
; __device__ __forceinline__ void block(const BlockRef& cur, const int j0, const int NT, const int split, const SplitRef sp, lptr lds, int tid) {
;     ...
;     SBAR(); qkt<1>(pB0, pB1, K_lds, r32, hi, qr); SBAR();
;     finishSM(pA0, pA1, alA, l_reg, pa0, pa1, pa2, pa3); SBAR();
;     pv_tile<0>(o, vb0, pa0, pa1, pa2, pa3);
.LBB0_885:
	s_mov_b32 s89, 0x20000
	ds_read_b128 v[82:85], v187 offset:49152
	ds_read_b128 v[86:89], v187 offset:57344
	s_waitcnt lgkmcnt(1)
	v_mfma_f32_32x32x16_bf16 v[98:113], v[82:85], v[142:145], 0
	s_waitcnt lgkmcnt(0)
	v_mfma_f32_32x32x16_bf16 v[82:97], v[86:89], v[142:145], 0
	ds_read_b128 v[142:145], v185 offset:49152
	ds_read_b128 v[176:179], v185 offset:57344
	s_waitcnt lgkmcnt(1)
	v_mfma_f32_32x32x16_bf16 v[98:113], v[142:145], v[138:141], v[98:113]
	s_waitcnt lgkmcnt(0)
	v_mfma_f32_32x32x16_bf16 v[82:97], v[176:179], v[138:141], v[82:97]
	ds_read_b128 v[138:141], v184 offset:49152
	ds_read_b128 v[142:145], v184 offset:57344
	s_waitcnt lgkmcnt(1)
	v_mfma_f32_32x32x16_bf16 v[98:113], v[138:141], v[134:137], v[98:113]
	s_waitcnt lgkmcnt(0)
	v_mfma_f32_32x32x16_bf16 v[82:97], v[142:145], v[134:137], v[82:97]
	ds_read_b128 v[134:137], v183 offset:49152
	ds_read_b128 v[138:141], v183 offset:57344
	s_waitcnt lgkmcnt(1)
	v_mfma_f32_32x32x16_bf16 v[98:113], v[134:137], v[130:133], v[98:113]
	s_waitcnt lgkmcnt(0)
	v_mfma_f32_32x32x16_bf16 v[82:97], v[138:141], v[130:133], v[82:97]
	ds_read_b128 v[130:133], v210 offset:49152
	ds_read_b128 v[134:137], v210 offset:57344
	s_waitcnt lgkmcnt(1)
	v_mfma_f32_32x32x16_bf16 v[98:113], v[130:133], v[126:129], v[98:113]
	s_waitcnt lgkmcnt(0)
	v_mfma_f32_32x32x16_bf16 v[82:97], v[134:137], v[126:129], v[82:97]
	ds_read_b128 v[126:129], v211 offset:49152
	ds_read_b128 v[130:133], v211 offset:57344
	s_waitcnt lgkmcnt(1)
	v_mfma_f32_32x32x16_bf16 v[98:113], v[126:129], v[122:125], v[98:113]
	s_waitcnt lgkmcnt(0)
	v_mfma_f32_32x32x16_bf16 v[82:97], v[130:133], v[122:125], v[82:97]
	ds_read_b128 v[122:125], v212 offset:49152
	ds_read_b128 v[126:129], v212 offset:57344
	s_waitcnt lgkmcnt(1)
	v_mfma_f32_32x32x16_bf16 v[98:113], v[122:125], v[118:121], v[98:113]
	s_waitcnt lgkmcnt(0)
	v_mfma_f32_32x32x16_bf16 v[82:97], v[126:129], v[118:121], v[82:97]
	ds_read_b128 v[118:121], v213 offset:49152
	ds_read_b128 v[122:125], v213 offset:57344
	s_waitcnt lgkmcnt(1)
	v_mfma_f32_32x32x16_bf16 v[98:113], v[118:121], v[114:117], v[98:113]
	s_waitcnt lgkmcnt(0)
	v_mfma_f32_32x32x16_bf16 v[82:97], v[122:125], v[114:117], v[82:97]
	v_exp_f32_e32 v123, v66
	v_add_f32_e32 v66, 0, v160
	v_add_f32_e32 v66, v227, v66
	v_add_f32_e32 v66, v158, v66
	v_add_f32_e32 v66, v161, v66
	v_add_f32_e32 v66, v157, v66
	v_add_f32_e32 v66, v159, v66
	v_add_f32_e32 v66, v155, v66
	v_add_f32_e32 v66, v156, v66
	v_add_f32_e32 v66, v152, v66
	v_add_f32_e32 v66, v154, v66
	v_add_f32_e32 v66, v151, v66
	v_add_f32_e32 v66, v153, v66
	v_exp_f32_e32 v80, v80
	v_add_f32_e32 v66, v148, v66
	v_exp_f32_e32 v1, v1
	v_add_f32_e32 v66, v150, v66
	v_exp_f32_e32 v78, v78
	v_add_f32_e32 v66, v147, v66
	v_exp_f32_e32 v79, v79
	v_add_f32_e32 v66, v149, v66
	v_exp_f32_e32 v76, v76
	v_add_f32_e32 v66, v80, v66
	v_exp_f32_e32 v77, v77
	v_add_f32_e32 v66, v1, v66
	v_exp_f32_e32 v81, v74
	v_add_f32_e32 v66, v78, v66
	v_exp_f32_e32 v116, v75
	v_add_f32_e32 v66, v79, v66
	v_exp_f32_e32 v117, v72
	v_add_f32_e32 v66, v76, v66
	v_exp_f32_e32 v118, v73
	v_add_f32_e32 v66, v77, v66
	v_exp_f32_e32 v119, v70
	v_add_f32_e32 v66, v81, v66
	v_exp_f32_e32 v120, v71
	v_add_f32_e32 v66, v116, v66
	v_exp_f32_e32 v121, v68
	v_add_f32_e32 v66, v117, v66
	v_exp_f32_e32 v122, v69
	v_add_f32_e32 v66, v118, v66
	v_add_f32_e32 v66, v119, v66
	v_exp_f32_e32 v124, v67
	v_add_f32_e32 v66, v120, v66
	v_add_f32_e32 v66, v121, v66
	v_add_f32_e32 v66, v122, v66
	v_add_f32_e32 v66, v123, v66
	v_add_f32_e32 v114, v124, v66
	v_mov_b32_e32 v115, v114
	v_cvt_pk_bf16_f32 v66, v160, v227
	v_cvt_pk_bf16_f32 v67, v158, v161
	v_cvt_pk_bf16_f32 v68, v157, v159
	v_cvt_pk_bf16_f32 v69, v155, v156
	v_cvt_pk_bf16_f32 v70, v152, v154
	v_cvt_pk_bf16_f32 v71, v151, v153
	v_cvt_pk_bf16_f32 v72, v148, v150
	v_cvt_pk_bf16_f32 v73, v147, v149
	v_cvt_pk_bf16_f32 v74, v80, v1
	v_cvt_pk_bf16_f32 v75, v78, v79
	v_cvt_pk_bf16_f32 v76, v76, v77
	v_cvt_pk_bf16_f32 v77, v81, v116
	v_cvt_pk_bf16_f32 v78, v117, v118
	v_cvt_pk_bf16_f32 v79, v119, v120
	v_cvt_pk_bf16_f32 v80, v121, v122
	v_cvt_pk_bf16_f32 v81, v123, v124
	s_nop 1
	v_permlane32_swap_b32_e32 v114, v115
	v_permlane32_swap_b32_e32 v66, v68
	v_permlane32_swap_b32_e32 v67, v69
	v_permlane32_swap_b32_e32 v70, v72
	v_permlane32_swap_b32_e32 v71, v73
	v_permlane32_swap_b32_e32 v74, v76
	v_permlane32_swap_b32_e32 v75, v77
	v_permlane32_swap_b32_e32 v78, v80
	v_permlane32_swap_b32_e32 v79, v81
	ds_read_b64_tr_b16 v[116:117], v181 offset:0
	ds_read_b64_tr_b16 v[118:119], v181 offset:0x800
	ds_read_b64_tr_b16 v[120:121], v181 offset:0x1000
	ds_read_b64_tr_b16 v[122:123], v181 offset:0x1800
	ds_read_b64_tr_b16 v[124:125], v181 offset:0x2000
	ds_read_b64_tr_b16 v[126:127], v181 offset:0x2800
	ds_read_b64_tr_b16 v[128:129], v181 offset:0x3000
	ds_read_b64_tr_b16 v[130:131], v181 offset:0x3800
	s_waitcnt lgkmcnt(0)
	s_nop 0
	v_mfma_f32_32x32x16_bf16 v[50:65], v[66:69], v[116:119], v[50:65]
	ds_read_b64_tr_b16 v[116:117], v181 offset:0x200
	ds_read_b64_tr_b16 v[118:119], v181 offset:0xa00
	v_mfma_f32_32x32x16_bf16 v[50:65], v[70:73], v[120:123], v[50:65]
	ds_read_b64_tr_b16 v[120:121], v181 offset:0x1200
	ds_read_b64_tr_b16 v[122:123], v181 offset:0x1a00
	v_mfma_f32_32x32x16_bf16 v[50:65], v[74:77], v[124:127], v[50:65]
	ds_read_b64_tr_b16 v[124:125], v181 offset:0x2200
	ds_read_b64_tr_b16 v[126:127], v181 offset:0x2a00
	v_mfma_f32_32x32x16_bf16 v[50:65], v[78:81], v[128:131], v[50:65]
	ds_read_b64_tr_b16 v[128:129], v181 offset:0x3200
	ds_read_b64_tr_b16 v[130:131], v181 offset:0x3a00
	s_waitcnt lgkmcnt(0)
; #define RESC(a) do { if (__any((a) < 1.f)) { if (hi == 0) al_l[r32] = (a); asm volatile("s_waitcnt lgkmcnt(0)" ::: "memory");              \
;                      _Pragma("unroll") for (int d_ = 0; d_ < 4; ++d_) _Pragma("unroll") for (int r = 0; r < 16; ++r) o[d_][r] *= al_l[crow(r, hi)]; } } while (0)
; #define MASKT(P0_, P1_, t) do { const int kb_ = KBASE(t); bias_tile(P0_, P1_, Cs + kb_); if (kb_ + KVBLK - 1 > qlo) mask_tile(P0_, P1_, qm - kb_); } while (0)
; template <int VB>
; __device__ __forceinline__ void pv_tile(f32x16* o, int vb0, bf16x8 pa0, bf16x8 pa1, bf16x8 pa2, bf16x8 pa3) {
;     ...
;     PV_D0(0); PV_D0(1); PV_D0(2); PV_D0(3);
; __device__ __forceinline__ void block(const BlockRef& cur, const int j0, const int NT, const int split, const SplitRef sp, lptr lds, int tid) {
;     ...
;     MASKT(pB0, pB1, NT - 1); partialSM(pB0, pB1, m_reg, alB); RESC(alB);
	v_mfma_f32_32x32x16_bf16 v[34:49], v[66:69], v[116:119], v[34:49]
	ds_read_b64_tr_b16 v[116:117], v181 offset:0x400
	ds_read_b64_tr_b16 v[118:119], v181 offset:0xc00
	v_mfma_f32_32x32x16_bf16 v[34:49], v[70:73], v[120:123], v[34:49]
	ds_read_b64_tr_b16 v[120:121], v181 offset:0x1400
	ds_read_b64_tr_b16 v[122:123], v181 offset:0x1c00
	v_mfma_f32_32x32x16_bf16 v[34:49], v[74:77], v[124:127], v[34:49]
	ds_read_b64_tr_b16 v[124:125], v181 offset:0x2400
	ds_read_b64_tr_b16 v[126:127], v181 offset:0x2c00
	v_mfma_f32_32x32x16_bf16 v[34:49], v[78:81], v[128:131], v[34:49]
	ds_read_b64_tr_b16 v[128:129], v181 offset:0x3400
	ds_read_b64_tr_b16 v[130:131], v181 offset:0x3c00
	s_waitcnt lgkmcnt(0)
	v_mfma_f32_32x32x16_bf16 v[18:33], v[66:69], v[116:119], v[18:33]
	ds_read_b64_tr_b16 v[116:117], v181 offset:0x600
	ds_read_b64_tr_b16 v[118:119], v181 offset:0xe00
	v_mfma_f32_32x32x16_bf16 v[18:33], v[70:73], v[120:123], v[18:33]
	ds_read_b64_tr_b16 v[120:121], v181 offset:0x1600
	ds_read_b64_tr_b16 v[122:123], v181 offset:0x1e00
	v_mfma_f32_32x32x16_bf16 v[18:33], v[74:77], v[124:127], v[18:33]
	ds_read_b64_tr_b16 v[124:125], v181 offset:0x2600
	ds_read_b64_tr_b16 v[126:127], v181 offset:0x2e00
	v_mfma_f32_32x32x16_bf16 v[18:33], v[78:81], v[128:131], v[18:33]
	ds_read_b64_tr_b16 v[128:129], v181 offset:0x3600
	ds_read_b64_tr_b16 v[130:131], v181 offset:0x3e00
	s_waitcnt lgkmcnt(0)
	v_mfma_f32_32x32x16_bf16 v[2:17], v[66:69], v[116:119], v[2:17]
	s_add_i32 s8, s82, s81
	s_add_i32 s9, s8, -1
	v_lshl_add_u32 v1, s9, 8, v182
	s_lshl_b32 s8, s9, 6
	s_or_b32 s9, s8, 63
	s_cmp_gt_i32 s9, s80
	v_mfma_f32_32x32x16_bf16 v[2:17], v[70:73], v[120:123], v[2:17]
	v_mfma_f32_32x32x16_bf16 v[2:17], v[74:77], v[124:127], v[2:17]
	v_mfma_f32_32x32x16_bf16 v[2:17], v[78:81], v[128:131], v[2:17]
	ds_read_b128 v[116:119], v1 offset:128
	ds_read_b128 v[78:81], v1
	ds_read_b128 v[74:77], v1 offset:32
	ds_read_b128 v[120:123], v1 offset:160
	ds_read_b128 v[124:127], v1 offset:64
	ds_read_b128 v[128:131], v1 offset:192
	ds_read_b128 v[68:71], v1 offset:96
	ds_read_b128 v[132:135], v1 offset:224
	s_waitcnt lgkmcnt(5)
	v_pk_fma_f32 v[72:73], v[102:103], s[2:3], v[74:75] op_sel_hi:[1,0,1]
	s_waitcnt lgkmcnt(3)
	v_pk_fma_f32 v[74:75], v[108:109], s[2:3], v[126:127] op_sel_hi:[1,0,1]
	v_pk_fma_f32 v[76:77], v[104:105], s[2:3], v[76:77] op_sel_hi:[1,0,1]
	s_waitcnt lgkmcnt(1)
	v_pk_fma_f32 v[66:67], v[110:111], s[2:3], v[68:69] op_sel_hi:[1,0,1]
	v_pk_fma_f32 v[68:69], v[106:107], s[2:3], v[124:125] op_sel_hi:[1,0,1]
	v_pk_fma_f32 v[70:71], v[112:113], s[2:3], v[70:71] op_sel_hi:[1,0,1]
	v_pk_fma_f32 v[80:81], v[100:101], s[2:3], v[80:81] op_sel_hi:[1,0,1]
	v_pk_fma_f32 v[98:99], v[98:99], s[2:3], v[78:79] op_sel_hi:[1,0,1]
	s_waitcnt lgkmcnt(0)
	v_pk_fma_f32 v[78:79], v[94:95], s[2:3], v[132:133] op_sel_hi:[1,0,1]
	v_pk_fma_f32 v[90:91], v[90:91], s[2:3], v[128:129] op_sel_hi:[1,0,1]
	v_pk_fma_f32 v[94:95], v[86:87], s[2:3], v[120:121] op_sel_hi:[1,0,1]
	v_pk_fma_f32 v[86:87], v[96:97], s[2:3], v[134:135] op_sel_hi:[1,0,1]
	v_pk_fma_f32 v[92:93], v[92:93], s[2:3], v[130:131] op_sel_hi:[1,0,1]
	v_pk_fma_f32 v[88:89], v[88:89], s[2:3], v[122:123] op_sel_hi:[1,0,1]
	v_pk_fma_f32 v[84:85], v[84:85], s[2:3], v[118:119] op_sel_hi:[1,0,1]
	v_pk_fma_f32 v[82:83], v[82:83], s[2:3], v[116:117] op_sel_hi:[1,0,1]
	s_cbranch_scc0 .LBB0_887
; __device__ __forceinline__ void mask_tile(f32x16& p0, f32x16& p1, int dq) {
;     const float NEG = -__builtin_inff();
; #pragma unroll
;     for (int r = 0; r < 16; ++r) { const int c = (r & 3) + 8 * (r >> 2);
;         if (dq - c < 0) p0[r] = NEG;
;         if (dq - c - 32 < 0) p1[r] = NEG; }
; }
	v_subrev_u32_e32 v1, s8, v180
	v_cmp_gt_i32_e64 s[68:69], 26, v1
	v_cmp_gt_i32_e64 s[70:71], 27, v1
	v_cmp_gt_i32_e64 s[66:67], 25, v1
	s_and_b64 s[68:69], s[70:71], s[68:69]
	v_cmp_gt_i32_e64 s[64:65], 24, v1
	s_and_b64 s[66:67], s[68:69], s[66:67]
	v_cmp_gt_i32_e64 s[62:63], 19, v1
	s_and_b64 s[64:65], s[66:67], s[64:65]
	v_cmp_gt_i32_e64 s[60:61], 18, v1
	s_and_b64 s[62:63], s[64:65], s[62:63]
	v_cmp_gt_i32_e64 s[58:59], 17, v1
	s_and_b64 s[60:61], s[62:63], s[60:61]
	v_cmp_gt_i32_e64 s[56:57], 16, v1
	s_and_b64 s[58:59], s[60:61], s[58:59]
	v_cmp_gt_i32_e64 s[54:55], 11, v1
	s_and_b64 s[56:57], s[58:59], s[56:57]
	v_cmp_gt_i32_e64 s[52:53], 10, v1
	s_and_b64 s[54:55], s[56:57], s[54:55]
	v_cmp_gt_i32_e64 s[50:51], 9, v1
	s_and_b64 s[52:53], s[54:55], s[52:53]
	v_cmp_gt_i32_e64 s[48:49], 8, v1
	s_and_b64 s[50:51], s[52:53], s[50:51]
	v_cmp_gt_i32_e64 s[46:47], 3, v1
	s_and_b64 s[48:49], s[50:51], s[48:49]
	v_cmp_gt_i32_e64 s[44:45], 2, v1
	s_and_b64 s[46:47], s[48:49], s[46:47]
	v_cmp_gt_i32_e64 s[42:43], 1, v1
	s_and_b64 s[44:45], s[46:47], s[44:45]
	v_cmp_gt_i32_e64 s[38:39], 0, v1
	s_and_b64 s[42:43], s[44:45], s[42:43]
	s_and_b64 s[38:39], s[42:43], s[38:39]
	v_cmp_gt_i32_e64 s[36:37], 58, v1
	v_cndmask_b32_e64 v98, v98, v206, s[38:39]
	v_cmp_gt_i32_e64 s[38:39], 59, v1
	v_cmp_gt_i32_e64 s[34:35], 57, v1
	s_and_b64 s[36:37], s[38:39], s[36:37]
	v_cmp_gt_i32_e64 s[30:31], 56, v1
	s_and_b64 s[34:35], s[36:37], s[34:35]
	v_cmp_gt_i32_e64 s[28:29], 51, v1
	s_and_b64 s[30:31], s[34:35], s[30:31]
	v_cmp_gt_i32_e64 s[26:27], 50, v1
	s_and_b64 s[28:29], s[30:31], s[28:29]
	v_cmp_gt_i32_e64 s[24:25], 49, v1
	s_and_b64 s[26:27], s[28:29], s[26:27]
	v_cmp_gt_i32_e64 s[22:23], 48, v1
	s_and_b64 s[24:25], s[26:27], s[24:25]
	v_cmp_gt_i32_e64 s[20:21], 43, v1
	s_and_b64 s[22:23], s[24:25], s[22:23]
	v_cmp_gt_i32_e64 s[18:19], 42, v1
	s_and_b64 s[20:21], s[22:23], s[20:21]
	v_cmp_gt_i32_e64 s[16:17], 41, v1
	s_and_b64 s[18:19], s[20:21], s[18:19]
	v_cmp_gt_i32_e64 s[14:15], 40, v1
	s_and_b64 s[16:17], s[18:19], s[16:17]
	v_cmp_gt_i32_e64 s[12:13], 35, v1
	s_and_b64 s[14:15], s[16:17], s[14:15]
	v_cmp_gt_i32_e64 s[10:11], 34, v1
	s_and_b64 s[12:13], s[14:15], s[12:13]
	v_cmp_gt_i32_e64 s[8:9], 33, v1
	s_and_b64 s[10:11], s[12:13], s[10:11]
	v_cmp_gt_i32_e32 vcc, 32, v1
	s_and_b64 s[8:9], s[10:11], s[8:9]
	s_and_b64 vcc, s[8:9], vcc
	v_cndmask_b32_e64 v71, v71, v206, s[70:71]
	v_cndmask_b32_e64 v70, v70, v206, s[68:69]
	v_cndmask_b32_e64 v67, v67, v206, s[66:67]
	v_cndmask_b32_e64 v66, v66, v206, s[64:65]
	v_cndmask_b32_e64 v75, v75, v206, s[62:63]
	v_cndmask_b32_e64 v74, v74, v206, s[60:61]
	v_cndmask_b32_e64 v69, v69, v206, s[58:59]
	v_cndmask_b32_e64 v68, v68, v206, s[56:57]
	v_cndmask_b32_e64 v77, v77, v206, s[54:55]
	v_cndmask_b32_e64 v76, v76, v206, s[52:53]
	v_cndmask_b32_e64 v73, v73, v206, s[50:51]
	v_cndmask_b32_e64 v72, v72, v206, s[48:49]
	v_cndmask_b32_e64 v81, v81, v206, s[46:47]
	v_cndmask_b32_e64 v80, v80, v206, s[44:45]
	v_cndmask_b32_e64 v99, v99, v206, s[42:43]
	v_cndmask_b32_e64 v87, v87, v206, s[38:39]
	v_cndmask_b32_e64 v86, v86, v206, s[36:37]
	v_cndmask_b32_e64 v79, v79, v206, s[34:35]
	v_cndmask_b32_e64 v78, v78, v206, s[30:31]
	v_cndmask_b32_e64 v93, v93, v206, s[28:29]
	v_cndmask_b32_e64 v92, v92, v206, s[26:27]
	v_cndmask_b32_e64 v91, v91, v206, s[24:25]
	v_cndmask_b32_e64 v90, v90, v206, s[22:23]
	v_cndmask_b32_e64 v89, v89, v206, s[20:21]
	v_cndmask_b32_e64 v88, v88, v206, s[18:19]
	v_cndmask_b32_e64 v95, v95, v206, s[16:17]
	v_cndmask_b32_e64 v94, v94, v206, s[14:15]
	v_cndmask_b32_e64 v85, v85, v206, s[12:13]
	v_cndmask_b32_e64 v84, v84, v206, s[10:11]
	v_cndmask_b32_e64 v83, v83, v206, s[8:9]
	v_cndmask_b32_e32 v82, v82, v206, vcc
